# pool phase: the 31 row loads per item issued back to back (79 per-row vmcnt(0) waits that only guarded reuse of the destination registers as address temporaries in disjoint lanes removed; one wait bef
# speedup vs baseline: 1.0053x; 1.0053x over previous
.LBB0_458:
	s_or_saveexec_b64 s[4:5], s[4:5]
	s_lshl_b32 s58, s3, 6
	s_add_i32 s58, s58, 0x10000
	s_lshl_b32 s38, s3, 13
	s_xor_b64 exec, exec, s[4:5]
	s_cbranch_execz .LBB0_468
	v_add_u32_e32 v1, -15, v158
	s_cmp_lt_i32 s50, 1
	s_mov_b64 s[6:7], -1
	s_cbranch_scc1 .LBB0_465
	s_cmp_lg_u32 s50, 1
	s_cbranch_scc0 .LBB0_462
	v_add_u32_e32 v0, 0x101f1, v158
	s_mov_b64 s[6:7], 0

.LBB0_475:
	s_andn2_saveexec_b64 s[4:5], s[4:5]
	s_cbranch_execz .LBB0_485
	v_add_u32_e32 v5, -14, v158
	s_cmp_lt_i32 s50, 1
	s_mov_b64 s[6:7], -1
	s_cbranch_scc1 .LBB0_482
	s_cmp_lg_u32 s50, 1
	s_cbranch_scc0 .LBB0_479
	v_add_u32_e32 v4, 0x101f2, v158
	s_mov_b64 s[6:7], 0

.LBB0_492:
	s_andn2_saveexec_b64 s[4:5], s[4:5]
	s_cbranch_execz .LBB0_502
	v_add_u32_e32 v11, -13, v158
	s_cmp_lt_i32 s50, 1
	s_mov_b64 s[6:7], -1
	s_cbranch_scc1 .LBB0_499
	s_cmp_lg_u32 s50, 1
	s_cbranch_scc0 .LBB0_496
	v_add_u32_e32 v10, 0x101f3, v158
	s_mov_b64 s[6:7], 0

.LBB0_509:
	s_andn2_saveexec_b64 s[4:5], s[4:5]
	s_cbranch_execz .LBB0_519
	v_add_u32_e32 v15, -12, v158
	s_cmp_lt_i32 s50, 1
	s_mov_b64 s[6:7], -1
	s_cbranch_scc1 .LBB0_516
	s_cmp_lg_u32 s50, 1
	s_cbranch_scc0 .LBB0_513
	v_add_u32_e32 v14, 0x101f4, v158
	s_mov_b64 s[6:7], 0

.LBB0_526:
	s_andn2_saveexec_b64 s[4:5], s[4:5]
	s_cbranch_execz .LBB0_536
	v_add_u32_e32 v19, -11, v158
	s_cmp_lt_i32 s50, 1
	s_mov_b64 s[6:7], -1
	s_cbranch_scc1 .LBB0_533
	s_cmp_lg_u32 s50, 1
	s_cbranch_scc0 .LBB0_530
	v_add_u32_e32 v18, 0x101f5, v158
	s_mov_b64 s[6:7], 0

.LBB0_543:
	s_andn2_saveexec_b64 s[4:5], s[4:5]
	s_cbranch_execz .LBB0_553
	v_add_u32_e32 v23, -10, v158
	s_cmp_lt_i32 s50, 1
	s_mov_b64 s[6:7], -1
	s_cbranch_scc1 .LBB0_550
	s_cmp_lg_u32 s50, 1
	s_cbranch_scc0 .LBB0_547
	v_add_u32_e32 v22, 0x101f6, v158
	s_mov_b64 s[6:7], 0

.LBB0_560:
	s_andn2_saveexec_b64 s[4:5], s[4:5]
	s_cbranch_execz .LBB0_570
	v_add_u32_e32 v27, -9, v158
	s_cmp_lt_i32 s50, 1
	s_mov_b64 s[6:7], -1
	s_cbranch_scc1 .LBB0_567
	s_cmp_lg_u32 s50, 1
	s_cbranch_scc0 .LBB0_564
	v_add_u32_e32 v26, 0x101f7, v158
	s_mov_b64 s[6:7], 0

.LBB0_577:
	s_andn2_saveexec_b64 s[4:5], s[4:5]
	s_cbranch_execz .LBB0_587
	v_add_u32_e32 v31, -8, v158
	s_cmp_lt_i32 s50, 1
	s_mov_b64 s[6:7], -1
	s_cbranch_scc1 .LBB0_584
	s_cmp_lg_u32 s50, 1
	s_cbranch_scc0 .LBB0_581
	v_add_u32_e32 v30, 0x101f8, v158
	s_mov_b64 s[6:7], 0

.LBB0_594:
	s_andn2_saveexec_b64 s[4:5], s[4:5]
	s_cbranch_execz .LBB0_604
	v_add_u32_e32 v35, -7, v158
	s_cmp_lt_i32 s50, 1
	s_mov_b64 s[6:7], -1
	s_cbranch_scc1 .LBB0_601
	s_cmp_lg_u32 s50, 1
	s_cbranch_scc0 .LBB0_598
	v_add_u32_e32 v34, 0x101f9, v158
	s_mov_b64 s[6:7], 0

.LBB0_611:
	s_andn2_saveexec_b64 s[4:5], s[4:5]
	s_cbranch_execz .LBB0_621
	v_add_u32_e32 v39, -6, v158
	s_cmp_lt_i32 s50, 1
	s_mov_b64 s[6:7], -1
	s_cbranch_scc1 .LBB0_618
	s_cmp_lg_u32 s50, 1
	s_cbranch_scc0 .LBB0_615
	v_add_u32_e32 v38, 0x101fa, v158
	s_mov_b64 s[6:7], 0

.LBB0_628:
	s_andn2_saveexec_b64 s[4:5], s[4:5]
	s_cbranch_execz .LBB0_638
	v_add_u32_e32 v43, -5, v158
	s_cmp_lt_i32 s50, 1
	s_mov_b64 s[6:7], -1
	s_cbranch_scc1 .LBB0_635
	s_cmp_lg_u32 s50, 1
	s_cbranch_scc0 .LBB0_632
	v_add_u32_e32 v42, 0x101fb, v158
	s_mov_b64 s[6:7], 0

.LBB0_645:
	s_andn2_saveexec_b64 s[4:5], s[4:5]
	s_cbranch_execz .LBB0_655
	v_add_u32_e32 v47, -4, v158
	s_cmp_lt_i32 s50, 1
	s_mov_b64 s[6:7], -1
	s_cbranch_scc1 .LBB0_652
	s_cmp_lg_u32 s50, 1
	s_cbranch_scc0 .LBB0_649
	v_add_u32_e32 v46, 0x101fc, v158
	s_mov_b64 s[6:7], 0

.LBB0_662:
	s_andn2_saveexec_b64 s[4:5], s[4:5]
	s_cbranch_execz .LBB0_672
	v_add_u32_e32 v51, -3, v158
	s_cmp_lt_i32 s50, 1
	s_mov_b64 s[6:7], -1
	s_cbranch_scc1 .LBB0_669
	s_cmp_lg_u32 s50, 1
	s_cbranch_scc0 .LBB0_666
	v_add_u32_e32 v50, 0x101fd, v158
	s_mov_b64 s[6:7], 0

.LBB0_679:
	s_andn2_saveexec_b64 s[4:5], s[4:5]
	s_cbranch_execz .LBB0_689
	v_add_u32_e32 v55, -2, v158
	s_cmp_lt_i32 s50, 1
	s_mov_b64 s[6:7], -1
	s_cbranch_scc1 .LBB0_686
	s_cmp_lg_u32 s50, 1
	s_cbranch_scc0 .LBB0_683
	v_add_u32_e32 v54, 0x101fe, v158
	s_mov_b64 s[6:7], 0

.LBB0_696:
	s_andn2_saveexec_b64 s[4:5], s[4:5]
	s_cbranch_execz .LBB0_706
	v_add_u32_e32 v59, -1, v158
	s_cmp_lt_i32 s50, 1
	s_mov_b64 s[6:7], -1
	s_cbranch_scc1 .LBB0_703
	s_cmp_lg_u32 s50, 1
	s_cbranch_scc0 .LBB0_700
	v_add_u32_e32 v58, 0x101ff, v158
	s_mov_b64 s[6:7], 0

.LBB0_713:
	s_andn2_saveexec_b64 s[4:5], s[4:5]
	s_cbranch_execz .LBB0_723
	s_cmp_lt_i32 s50, 1
	s_mov_b64 s[6:7], -1
	s_cbranch_scc1 .LBB0_720
	s_cmp_lg_u32 s50, 1
	s_cbranch_scc0 .LBB0_717
	v_add_u32_e32 v62, 0x10200, v158
	s_mov_b64 s[6:7], 0
.LBB0_717:
	s_andn2_b64 vcc, exec, s[6:7]
	s_cbranch_vccnz .LBB0_719
	v_add_u32_e32 v62, s58, v158

.LBB0_720:
	s_andn2_b64 vcc, exec, s[6:7]
	s_cbranch_vccnz .LBB0_722
	v_add_u32_e32 v62, s38, v158
.LBB0_722:
	v_ashrrev_i32_e32 v63, 31, v62
	v_lshlrev_b64 v[62:63], 11, v[62:63]
	v_lshl_add_u64 v[62:63], v[152:153], 0, v[62:63]
	global_load_dwordx4 v[62:65], v[62:63], off

.LBB0_730:
	s_or_saveexec_b64 s[4:5], s[4:5]
	v_or_b32_e32 v186, 1, v158
	s_xor_b64 exec, exec, s[4:5]
	s_cbranch_execz .LBB0_740
	s_cmp_lt_i32 s50, 1
	s_mov_b64 s[6:7], -1
	s_cbranch_scc1 .LBB0_737
	s_cmp_lg_u32 s50, 1
	s_cbranch_scc0 .LBB0_734
	v_add_u32_e32 v66, 0x10201, v158
	s_mov_b64 s[6:7], 0
.LBB0_734:
	s_andn2_b64 vcc, exec, s[6:7]
	s_cbranch_vccnz .LBB0_736
	v_add_u32_e32 v66, s58, v186

.LBB0_737:
	s_andn2_b64 vcc, exec, s[6:7]
	s_cbranch_vccnz .LBB0_739
	v_add_u32_e32 v66, s38, v186
.LBB0_739:
	v_ashrrev_i32_e32 v67, 31, v66
	v_lshlrev_b64 v[66:67], 11, v[66:67]
	v_lshl_add_u64 v[66:67], v[152:153], 0, v[66:67]
	global_load_dwordx4 v[66:69], v[66:67], off

.LBB0_747:
	s_or_saveexec_b64 s[4:5], s[4:5]
	v_or_b32_e32 v188, 2, v158
	s_xor_b64 exec, exec, s[4:5]
	s_cbranch_execz .LBB0_757
	s_cmp_lt_i32 s50, 1
	s_mov_b64 s[6:7], -1
	s_cbranch_scc1 .LBB0_754
	s_cmp_lg_u32 s50, 1
	s_cbranch_scc0 .LBB0_751
	v_add_u32_e32 v70, 0x10202, v158
	s_mov_b64 s[6:7], 0
.LBB0_751:
	s_andn2_b64 vcc, exec, s[6:7]
	s_cbranch_vccnz .LBB0_753
	v_add_u32_e32 v70, s58, v188

.LBB0_754:
	s_andn2_b64 vcc, exec, s[6:7]
	s_cbranch_vccnz .LBB0_756
	v_add_u32_e32 v70, s38, v188
.LBB0_756:
	v_ashrrev_i32_e32 v71, 31, v70
	v_lshlrev_b64 v[70:71], 11, v[70:71]
	v_lshl_add_u64 v[70:71], v[152:153], 0, v[70:71]
	global_load_dwordx4 v[70:73], v[70:71], off

.LBB0_764:
	s_or_saveexec_b64 s[4:5], s[4:5]
	v_or_b32_e32 v185, 3, v158
	s_xor_b64 exec, exec, s[4:5]
	s_cbranch_execz .LBB0_774
	s_cmp_lt_i32 s50, 1
	s_mov_b64 s[6:7], -1
	s_cbranch_scc1 .LBB0_771
	s_cmp_lg_u32 s50, 1
	s_cbranch_scc0 .LBB0_768
	v_add_u32_e32 v74, 0x10203, v158
	s_mov_b64 s[6:7], 0
.LBB0_768:
	s_andn2_b64 vcc, exec, s[6:7]
	s_cbranch_vccnz .LBB0_770
	v_add_u32_e32 v74, s58, v185

.LBB0_771:
	s_andn2_b64 vcc, exec, s[6:7]
	s_cbranch_vccnz .LBB0_773
	v_add_u32_e32 v74, s38, v185
.LBB0_773:
	v_ashrrev_i32_e32 v75, 31, v74
	v_lshlrev_b64 v[74:75], 11, v[74:75]
	v_lshl_add_u64 v[74:75], v[152:153], 0, v[74:75]
	global_load_dwordx4 v[74:77], v[74:75], off

.LBB0_781:
	s_or_saveexec_b64 s[4:5], s[4:5]
	v_or_b32_e32 v190, 4, v158
	s_xor_b64 exec, exec, s[4:5]
	s_cbranch_execz .LBB0_791
	s_cmp_lt_i32 s50, 1
	s_mov_b64 s[6:7], -1
	s_cbranch_scc1 .LBB0_788
	s_cmp_lg_u32 s50, 1
	s_cbranch_scc0 .LBB0_785
	v_add_u32_e32 v78, 0x10204, v158
	s_mov_b64 s[6:7], 0
.LBB0_785:
	s_andn2_b64 vcc, exec, s[6:7]
	s_cbranch_vccnz .LBB0_787
	v_add_u32_e32 v78, s58, v190

.LBB0_788:
	s_andn2_b64 vcc, exec, s[6:7]
	s_cbranch_vccnz .LBB0_790
	v_add_u32_e32 v78, s38, v190
.LBB0_790:
	v_ashrrev_i32_e32 v79, 31, v78
	v_lshlrev_b64 v[78:79], 11, v[78:79]
	v_lshl_add_u64 v[78:79], v[152:153], 0, v[78:79]
	global_load_dwordx4 v[78:81], v[78:79], off

.LBB0_798:
	s_or_saveexec_b64 s[4:5], s[4:5]
	v_or_b32_e32 v187, 5, v158
	s_xor_b64 exec, exec, s[4:5]
	s_cbranch_execz .LBB0_808
	s_cmp_lt_i32 s50, 1
	s_mov_b64 s[6:7], -1
	s_cbranch_scc1 .LBB0_805
	s_cmp_lg_u32 s50, 1
	s_cbranch_scc0 .LBB0_802
	v_add_u32_e32 v82, 0x10205, v158
	s_mov_b64 s[6:7], 0
.LBB0_802:
	s_andn2_b64 vcc, exec, s[6:7]
	s_cbranch_vccnz .LBB0_804
	v_add_u32_e32 v82, s58, v187

.LBB0_805:
	s_andn2_b64 vcc, exec, s[6:7]
	s_cbranch_vccnz .LBB0_807
	v_add_u32_e32 v82, s38, v187
.LBB0_807:
	v_ashrrev_i32_e32 v83, 31, v82
	v_lshlrev_b64 v[82:83], 11, v[82:83]
	v_lshl_add_u64 v[82:83], v[152:153], 0, v[82:83]
	global_load_dwordx4 v[82:85], v[82:83], off

.LBB0_815:
	s_or_saveexec_b64 s[4:5], s[4:5]
	v_or_b32_e32 v189, 6, v158
	s_xor_b64 exec, exec, s[4:5]
	s_cbranch_execz .LBB0_825
	s_cmp_lt_i32 s50, 1
	s_mov_b64 s[6:7], -1
	s_cbranch_scc1 .LBB0_822
	s_cmp_lg_u32 s50, 1
	s_cbranch_scc0 .LBB0_819
	v_add_u32_e32 v86, 0x10206, v158
	s_mov_b64 s[6:7], 0
.LBB0_819:
	s_andn2_b64 vcc, exec, s[6:7]
	s_cbranch_vccnz .LBB0_821
	v_add_u32_e32 v86, s58, v189

.LBB0_822:
	s_andn2_b64 vcc, exec, s[6:7]
	s_cbranch_vccnz .LBB0_824
	v_add_u32_e32 v86, s38, v189
.LBB0_824:
	v_ashrrev_i32_e32 v87, 31, v86
	v_lshlrev_b64 v[86:87], 11, v[86:87]
	v_lshl_add_u64 v[86:87], v[152:153], 0, v[86:87]
	global_load_dwordx4 v[86:89], v[86:87], off

.LBB0_832:
	s_or_saveexec_b64 s[4:5], s[4:5]
	v_or_b32_e32 v191, 7, v158
	s_xor_b64 exec, exec, s[4:5]
	s_cbranch_execz .LBB0_842
	s_cmp_lt_i32 s50, 1
	s_mov_b64 s[6:7], -1
	s_cbranch_scc1 .LBB0_839
	s_cmp_lg_u32 s50, 1
	s_cbranch_scc0 .LBB0_836
	v_add_u32_e32 v90, 0x10207, v158
	s_mov_b64 s[6:7], 0
.LBB0_836:
	s_andn2_b64 vcc, exec, s[6:7]
	s_cbranch_vccnz .LBB0_838
	v_add_u32_e32 v90, s58, v191

.LBB0_839:
	s_andn2_b64 vcc, exec, s[6:7]
	s_cbranch_vccnz .LBB0_841
	v_add_u32_e32 v90, s38, v191
.LBB0_841:
	v_ashrrev_i32_e32 v91, 31, v90
	v_lshlrev_b64 v[90:91], 11, v[90:91]
	v_lshl_add_u64 v[90:91], v[152:153], 0, v[90:91]
	global_load_dwordx4 v[90:93], v[90:91], off

.LBB0_849:
	s_or_saveexec_b64 s[4:5], s[4:5]
	v_or_b32_e32 v196, 8, v158
	s_xor_b64 exec, exec, s[4:5]
	s_cbranch_execz .LBB0_859
	s_cmp_lt_i32 s50, 1
	s_mov_b64 s[6:7], -1
	s_cbranch_scc1 .LBB0_856
	s_cmp_lg_u32 s50, 1
	s_cbranch_scc0 .LBB0_853
	v_add_u32_e32 v94, 0x10208, v158
	s_mov_b64 s[6:7], 0
.LBB0_853:
	s_andn2_b64 vcc, exec, s[6:7]
	s_cbranch_vccnz .LBB0_855
	v_add_u32_e32 v94, s58, v196

.LBB0_856:
	s_andn2_b64 vcc, exec, s[6:7]
	s_cbranch_vccnz .LBB0_858
	v_add_u32_e32 v94, s38, v196
.LBB0_858:
	v_ashrrev_i32_e32 v95, 31, v94
	v_lshlrev_b64 v[94:95], 11, v[94:95]
	v_lshl_add_u64 v[94:95], v[152:153], 0, v[94:95]
	global_load_dwordx4 v[94:97], v[94:95], off

.LBB0_866:
	s_or_saveexec_b64 s[4:5], s[4:5]
	v_or_b32_e32 v192, 9, v158
	s_xor_b64 exec, exec, s[4:5]
	s_cbranch_execz .LBB0_876
	s_cmp_lt_i32 s50, 1
	s_mov_b64 s[6:7], -1
	s_cbranch_scc1 .LBB0_873
	s_cmp_lg_u32 s50, 1
	s_cbranch_scc0 .LBB0_870
	v_add_u32_e32 v98, 0x10209, v158
	s_mov_b64 s[6:7], 0
.LBB0_870:
	s_andn2_b64 vcc, exec, s[6:7]
	s_cbranch_vccnz .LBB0_872
	v_add_u32_e32 v98, s58, v192

.LBB0_873:
	s_andn2_b64 vcc, exec, s[6:7]
	s_cbranch_vccnz .LBB0_875
	v_add_u32_e32 v98, s38, v192
.LBB0_875:
	v_ashrrev_i32_e32 v99, 31, v98
	v_lshlrev_b64 v[98:99], 11, v[98:99]
	v_lshl_add_u64 v[98:99], v[152:153], 0, v[98:99]
	global_load_dwordx4 v[98:101], v[98:99], off

.LBB0_883:
	s_or_saveexec_b64 s[4:5], s[4:5]
	v_or_b32_e32 v193, 10, v158
	s_xor_b64 exec, exec, s[4:5]
	s_cbranch_execz .LBB0_893
	s_cmp_lt_i32 s50, 1
	s_mov_b64 s[6:7], -1
	s_cbranch_scc1 .LBB0_890
	s_cmp_lg_u32 s50, 1
	s_cbranch_scc0 .LBB0_887
	v_add_u32_e32 v102, 0x1020a, v158
	s_mov_b64 s[6:7], 0
.LBB0_887:
	s_andn2_b64 vcc, exec, s[6:7]
	s_cbranch_vccnz .LBB0_889
	v_add_u32_e32 v102, s58, v193

.LBB0_890:
	s_andn2_b64 vcc, exec, s[6:7]
	s_cbranch_vccnz .LBB0_892
	v_add_u32_e32 v102, s38, v193
.LBB0_892:
	v_ashrrev_i32_e32 v103, 31, v102
	v_lshlrev_b64 v[102:103], 11, v[102:103]
	v_lshl_add_u64 v[102:103], v[152:153], 0, v[102:103]
	global_load_dwordx4 v[102:105], v[102:103], off

.LBB0_900:
	s_or_saveexec_b64 s[4:5], s[4:5]
	v_or_b32_e32 v194, 11, v158
	s_xor_b64 exec, exec, s[4:5]
	s_cbranch_execz .LBB0_910
	s_cmp_lt_i32 s50, 1
	s_mov_b64 s[6:7], -1
	s_cbranch_scc1 .LBB0_907
	s_cmp_lg_u32 s50, 1
	s_cbranch_scc0 .LBB0_904
	v_add_u32_e32 v106, 0x1020b, v158
	s_mov_b64 s[6:7], 0
.LBB0_904:
	s_andn2_b64 vcc, exec, s[6:7]
	s_cbranch_vccnz .LBB0_906
	v_add_u32_e32 v106, s58, v194

.LBB0_907:
	s_andn2_b64 vcc, exec, s[6:7]
	s_cbranch_vccnz .LBB0_909
	v_add_u32_e32 v106, s38, v194
.LBB0_909:
	v_ashrrev_i32_e32 v107, 31, v106
	v_lshlrev_b64 v[106:107], 11, v[106:107]
	v_lshl_add_u64 v[106:107], v[152:153], 0, v[106:107]
	global_load_dwordx4 v[106:109], v[106:107], off

.LBB0_917:
	s_or_saveexec_b64 s[4:5], s[4:5]
	v_or_b32_e32 v195, 12, v158
	s_xor_b64 exec, exec, s[4:5]
	s_cbranch_execz .LBB0_927
	s_cmp_lt_i32 s50, 1
	s_mov_b64 s[6:7], -1
	s_cbranch_scc1 .LBB0_924
	s_cmp_lg_u32 s50, 1
	s_cbranch_scc0 .LBB0_921
	v_add_u32_e32 v110, 0x1020c, v158
	s_mov_b64 s[6:7], 0
.LBB0_921:
	s_andn2_b64 vcc, exec, s[6:7]
	s_cbranch_vccnz .LBB0_923
	v_add_u32_e32 v110, s58, v195

.LBB0_924:
	s_andn2_b64 vcc, exec, s[6:7]
	s_cbranch_vccnz .LBB0_926
	v_add_u32_e32 v110, s38, v195
.LBB0_926:
	v_ashrrev_i32_e32 v111, 31, v110
	v_lshlrev_b64 v[110:111], 11, v[110:111]
	v_lshl_add_u64 v[110:111], v[152:153], 0, v[110:111]
	global_load_dwordx4 v[110:113], v[110:111], off

.LBB0_934:
	s_or_saveexec_b64 s[4:5], s[4:5]
	v_or_b32_e32 v197, 13, v158
	s_xor_b64 exec, exec, s[4:5]
	s_cbranch_execz .LBB0_944
	s_cmp_lt_i32 s50, 1
	s_mov_b64 s[6:7], -1
	s_cbranch_scc1 .LBB0_941
	s_cmp_lg_u32 s50, 1
	s_cbranch_scc0 .LBB0_938
	v_add_u32_e32 v114, 0x1020d, v158
	s_mov_b64 s[6:7], 0
.LBB0_938:
	s_andn2_b64 vcc, exec, s[6:7]
	s_cbranch_vccnz .LBB0_940
	v_add_u32_e32 v114, s58, v197

.LBB0_941:
	s_andn2_b64 vcc, exec, s[6:7]
	s_cbranch_vccnz .LBB0_943
	v_add_u32_e32 v114, s38, v197
.LBB0_943:
	v_ashrrev_i32_e32 v115, 31, v114
	v_lshlrev_b64 v[114:115], 11, v[114:115]
	v_lshl_add_u64 v[114:115], v[152:153], 0, v[114:115]
	global_load_dwordx4 v[114:117], v[114:115], off

.LBB0_951:
	s_or_saveexec_b64 s[4:5], s[4:5]
	v_or_b32_e32 v225, 14, v158
	s_xor_b64 exec, exec, s[4:5]
	s_cbranch_execz .LBB0_961
	s_cmp_lt_i32 s50, 1
	s_mov_b64 s[6:7], -1
	s_cbranch_scc1 .LBB0_958
	s_cmp_lg_u32 s50, 1
	s_cbranch_scc0 .LBB0_955
	v_add_u32_e32 v118, 0x1020e, v158
	s_mov_b64 s[6:7], 0
.LBB0_955:
	s_andn2_b64 vcc, exec, s[6:7]
	s_cbranch_vccnz .LBB0_957
	v_add_u32_e32 v118, s58, v225

.LBB0_958:
	s_andn2_b64 vcc, exec, s[6:7]
	s_cbranch_vccnz .LBB0_960
	v_add_u32_e32 v118, s38, v225
.LBB0_960:
	v_ashrrev_i32_e32 v119, 31, v118
	v_lshlrev_b64 v[118:119], 11, v[118:119]
	v_lshl_add_u64 v[118:119], v[152:153], 0, v[118:119]
	global_load_dwordx4 v[118:121], v[118:119], off

.LBB0_968:
	s_or_saveexec_b64 s[4:5], s[4:5]
	v_or_b32_e32 v159, 15, v158
	s_xor_b64 exec, exec, s[4:5]
	s_cbranch_execz .LBB0_978
	s_cmp_lt_i32 s50, 1
	s_mov_b64 s[6:7], -1
	s_cbranch_scc1 .LBB0_975
	s_cmp_lg_u32 s50, 1
	s_cbranch_scc0 .LBB0_972
	v_add_u32_e32 v122, 0x1020f, v158
	s_mov_b64 s[6:7], 0
.LBB0_972:
	s_andn2_b64 vcc, exec, s[6:7]
	s_cbranch_vccnz .LBB0_974
	v_add_u32_e32 v122, s58, v159

.LBB0_975:
	s_andn2_b64 vcc, exec, s[6:7]
	s_cbranch_vccnz .LBB0_977
	v_add_u32_e32 v122, s38, v159
.LBB0_977:
	v_ashrrev_i32_e32 v123, 31, v122
	v_lshlrev_b64 v[122:123], 11, v[122:123]
	v_lshl_add_u64 v[122:123], v[152:153], 0, v[122:123]
	global_load_dwordx4 v[122:125], v[122:123], off
